# speedup vs baseline: 1.0045x; 1.0045x over previous
; #define LAS __attribute__((address_space(3)))
; __device__ __forceinline__ unsigned pk2(float lo, float hi) { return f2bf(lo) | (f2bf(hi) << 16); }
; template <int KIND, int MODE>
; __device__ __forceinline__ void scan_unit(Frame& F, int layer, int h, int vhalf, int grp) {
;     ...
;             for (int i = 0; i < 4; ++i) { const int c = tid + 512 * i, t = c >> 5, dc = (c & 31) * 8; const float wa = X[192 + t];
;                 const u32x4 k = pk[i]; u32x4 ko;
;                 if (MODE == 1) { const u32x4 q = qr[i]; u32x4 qo; qo.x = pk2(bflo(q.x) * 0.0625f, bfhi(q.x) * 0.0625f); qo.y = pk2(bflo(q.y) * 0.0625f, bfhi(q.y) * 0.0625f); qo.z = pk2(bflo(q.z) * 0.0625f, bfhi(q.z) * 0.0625f); qo.w = pk2(bflo(q.w) * 0.0625f, bfhi(q.w) * 0.0625f);
;                     *(LAS u32x4*)(QS + t * QST + dc) = qo; *(LAS u32x4*)(KS + t * QST + dc) = k; }
;                 ko.x = pk2(bflo(k.x) * wa, bfhi(k.x) * wa); ko.y = pk2(bflo(k.y) * wa, bfhi(k.y) * wa); ko.z = pk2(bflo(k.z) * wa, bfhi(k.z) * wa); ko.w = pk2(bflo(k.w) * wa, bfhi(k.w) * wa);
;                 *(LAS u32x4*)(K2 + t * QST + dc) = ko; }
;             if (PREF && ch + 1 < (grp + 1) * GC) SCAN_LOAD(tb + 64);
.LBB0_409:
	s_waitcnt lgkmcnt(0)
	s_barrier
	ds_read_b32 v0, v115 offset:768
	v_and_b32_e32 v93, 0xffff0000, v15
	v_and_b32_e32 v92, 0xffff0000, v14
	v_and_b32_e32 v97, 0xffff0000, v17
	v_and_b32_e32 v96, 0xffff0000, v16
	v_lshlrev_b32_e32 v91, 16, v15
	v_lshlrev_b32_e32 v90, 16, v14
	s_waitcnt lgkmcnt(0)
	v_pk_mul_f32 v[92:93], v[0:1], v[92:93] op_sel_hi:[0,1]
	v_lshlrev_b32_e32 v95, 16, v17
	v_lshlrev_b32_e32 v94, 16, v16
	v_pk_mul_f32 v[96:97], v[0:1], v[96:97] op_sel_hi:[0,1]
	v_pk_mul_f32 v[90:91], v[0:1], v[90:91] op_sel_hi:[0,1]
	v_pk_mul_f32 v[94:95], v[0:1], v[94:95] op_sel_hi:[0,1]
	v_cvt_pk_bf16_f32 v91, v91, v93
	v_cvt_pk_bf16_f32 v90, v90, v92
	v_cvt_pk_bf16_f32 v92, v94, v96
	v_cvt_pk_bf16_f32 v93, v95, v97
	ds_write_b128 v122, v[90:93]
	ds_read_b32 v0, v116 offset:768
	v_and_b32_e32 v93, 0xffff0000, v19
	v_and_b32_e32 v92, 0xffff0000, v18
	v_and_b32_e32 v97, 0xffff0000, v21
	v_and_b32_e32 v96, 0xffff0000, v20
	v_lshlrev_b32_e32 v91, 16, v19
	v_lshlrev_b32_e32 v90, 16, v18
	s_waitcnt lgkmcnt(0)
	v_pk_mul_f32 v[92:93], v[0:1], v[92:93] op_sel_hi:[0,1]
	v_lshlrev_b32_e32 v95, 16, v21
	v_lshlrev_b32_e32 v94, 16, v20
	v_pk_mul_f32 v[96:97], v[0:1], v[96:97] op_sel_hi:[0,1]
	v_pk_mul_f32 v[90:91], v[0:1], v[90:91] op_sel_hi:[0,1]
	v_pk_mul_f32 v[94:95], v[0:1], v[94:95] op_sel_hi:[0,1]
	v_cvt_pk_bf16_f32 v91, v91, v93
	v_cvt_pk_bf16_f32 v90, v90, v92
	v_cvt_pk_bf16_f32 v92, v94, v96
	v_cvt_pk_bf16_f32 v93, v95, v97
	ds_write_b128 v123, v[90:93]
	ds_read_b32 v0, v117 offset:768
	v_and_b32_e32 v93, 0xffff0000, v27
	v_and_b32_e32 v92, 0xffff0000, v26
	v_and_b32_e32 v97, 0xffff0000, v29
	v_and_b32_e32 v96, 0xffff0000, v28
	v_lshlrev_b32_e32 v91, 16, v27
	v_lshlrev_b32_e32 v90, 16, v26
	s_waitcnt lgkmcnt(0)
	v_pk_mul_f32 v[92:93], v[0:1], v[92:93] op_sel_hi:[0,1]
	v_lshlrev_b32_e32 v95, 16, v29
	v_lshlrev_b32_e32 v94, 16, v28
	v_pk_mul_f32 v[96:97], v[0:1], v[96:97] op_sel_hi:[0,1]
	v_pk_mul_f32 v[90:91], v[0:1], v[90:91] op_sel_hi:[0,1]
	v_pk_mul_f32 v[94:95], v[0:1], v[94:95] op_sel_hi:[0,1]
	v_cvt_pk_bf16_f32 v91, v91, v93
	v_cvt_pk_bf16_f32 v90, v90, v92
	v_cvt_pk_bf16_f32 v92, v94, v96
	v_cvt_pk_bf16_f32 v93, v95, v97
	ds_write_b128 v124, v[90:93]
	ds_read_b32 v0, v118 offset:768
	v_and_b32_e32 v93, 0xffff0000, v35
	v_and_b32_e32 v92, 0xffff0000, v34
	v_and_b32_e32 v97, 0xffff0000, v37
	v_and_b32_e32 v96, 0xffff0000, v36
	v_lshlrev_b32_e32 v91, 16, v35
	v_lshlrev_b32_e32 v90, 16, v34
	s_waitcnt lgkmcnt(0)
	v_pk_mul_f32 v[92:93], v[0:1], v[92:93] op_sel_hi:[0,1]
	v_lshlrev_b32_e32 v95, 16, v37
	v_lshlrev_b32_e32 v94, 16, v36
	v_pk_mul_f32 v[96:97], v[0:1], v[96:97] op_sel_hi:[0,1]
	v_pk_mul_f32 v[90:91], v[0:1], v[90:91] op_sel_hi:[0,1]
	v_pk_mul_f32 v[94:95], v[0:1], v[94:95] op_sel_hi:[0,1]
	v_bfe_u32 v0, v97, 16, 1
	v_bfe_u32 v128, v96, 16, 1
	v_bfe_u32 v129, v93, 16, 1
	v_bfe_u32 v130, v92, 16, 1
	v_add3_u32 v130, v92, v130, s81
	v_add3_u32 v129, v93, v129, s81
	v_add3_u32 v92, v96, v128, s81
	v_add3_u32 v0, v97, v0, s81
	v_bfe_u32 v93, v90, 16, 1
	v_bfe_u32 v96, v91, 16, 1
	v_bfe_u32 v97, v94, 16, 1
	v_bfe_u32 v128, v95, 16, 1
	v_add3_u32 v95, v95, v128, s81
	v_add3_u32 v94, v94, v97, s81
	v_add3_u32 v91, v91, v96, s81
	v_add3_u32 v90, v90, v93, s81
	v_lshrrev_b32_e32 v90, 16, v90
	v_lshrrev_b32_e32 v91, 16, v91
	v_lshrrev_b32_e32 v94, 16, v94
	v_lshrrev_b32_e32 v93, 16, v95
	s_add_i32 s0, s97, 1
	v_and_or_b32 v93, v0, s46, v93
	v_and_or_b32 v92, v92, s46, v94
	v_and_or_b32 v91, v129, s46, v91
	v_and_or_b32 v90, v130, s46, v90
	s_cmp_ge_i32 s0, s96
	ds_write_b128 v125, v[90:93]
	s_cbranch_scc1 .LBB0_412
	s_lshl_b32 s1, s97, 6
	s_add_i32 s41, s1, 64
	v_add_u32_e32 v6, s41, v99
	v_add_u32_e32 v8, s41, v105
	v_add_u32_e32 v14, s41, v106
	v_add_u32_e32 v16, s41, v107
	v_add_u32_e32 v26, s41, v108
	v_add_u32_e32 v28, s41, v109
	v_ashrrev_i32_e32 v7, 31, v6
	v_ashrrev_i32_e32 v9, 31, v8
	v_ashrrev_i32_e32 v15, 31, v14
	v_ashrrev_i32_e32 v17, 31, v16
	v_ashrrev_i32_e32 v27, 31, v26
	v_ashrrev_i32_e32 v29, 31, v28
	v_lshlrev_b64 v[6:7], 11, v[6:7]
	v_lshlrev_b64 v[8:9], 11, v[8:9]
	v_lshlrev_b64 v[14:15], 11, v[14:15]
	v_lshlrev_b64 v[16:17], 11, v[16:17]
	v_lshlrev_b64 v[26:27], 11, v[26:27]
	v_lshlrev_b64 v[28:29], 11, v[28:29]
	v_lshl_add_u64 v[6:7], v[100:101], 0, v[6:7]
	v_lshl_add_u64 v[10:11], v[100:101], 0, v[8:9]
	v_lshl_add_u64 v[14:15], v[102:103], 0, v[14:15]
	v_lshl_add_u64 v[18:19], v[102:103], 0, v[16:17]
	v_lshl_add_u64 v[26:27], v[102:103], 0, v[26:27]
	v_lshl_add_u64 v[34:35], v[102:103], 0, v[28:29]
	flat_load_dwordx4 v[6:9], v[6:7]
	s_nop 0
	flat_load_dwordx4 v[10:13], v[10:11]
	s_nop 0
	flat_load_dwordx4 v[14:17], v[14:15]
	s_nop 0
	flat_load_dwordx4 v[18:21], v[18:19]
	s_nop 0
	flat_load_dwordx4 v[26:29], v[26:27]
	s_nop 0
	flat_load_dwordx4 v[34:37], v[34:35]
	s_and_b64 vcc, exec, s[24:25]
	s_cbranch_vccnz .LBB0_412
	v_add_u32_e32 v90, s1, v113
	v_ashrrev_i32_e32 v91, 31, v90
	v_lshlrev_b64 v[90:91], 5, v[90:91]
	v_lshl_add_u64 v[90:91], s[52:53], 0, v[90:91]
	flat_load_dword v111, v[90:91] offset:16
	flat_load_dword v112, v[90:91]
